# grid barrier: workgroups that are not their XCD's last arriver poll the top-level generation word directly instead of waiting for the per-XCD generation relay; the per-XCD relay add is gone
# speedup vs baseline: 1.0094x; 1.0036x over previous
; __device__ __forceinline__ unsigned xb_ld(unsigned* p)              { return __hip_atomic_load(p, __ATOMIC_RELAXED, __HIP_MEMORY_SCOPE_AGENT); }
; __device__ __forceinline__ unsigned xb_add(unsigned* p, unsigned v) { return __hip_atomic_fetch_add(p, v, __ATOMIC_RELAXED, __HIP_MEMORY_SCOPE_AGENT); }
; #define XB_SPIN(cond, bar) do { unsigned _sp = 0; while (cond) { __builtin_amdgcn_s_sleep(1); \
;     if ((++_sp & 255u) == 0u) { if (xb_ld(&(bar)[XB_TMO])) break; if (_sp > XB_SPIN_CAP) { atomicAdd(&(bar)[XB_TMO], 1u); break; } } } } while (0)
; __device__ __forceinline__ void xcd_barrier(const XcdBarrier& b) {
;     ...
;         const unsigned old = xb_add(&bar[XB_XSUB(b.x)], 1u);
;         const unsigned gen = old / nloc;
;         if (old + 1u == (gen + 1u) * nloc) {
;             __builtin_amdgcn_fence(__ATOMIC_RELEASE, "agent");
;             asm volatile("s_waitcnt vmcnt(0)" ::: "memory");
;             const unsigned og = xb_add(&bar[XB_TOP], 1u);
;             const unsigned tg = og / nx;
;             if (og + 1u == (tg + 1u) * nx) xb_add(&bar[XB_TOPGEN], 1u);
;             else XB_SPIN(xb_ld(&bar[XB_TOPGEN]) == tg, bar);
;             __builtin_amdgcn_fence(__ATOMIC_ACQUIRE, "agent");
;             xb_add(&bar[XB_XGEN(b.x)], 1u);
;             asm volatile("s_waitcnt vmcnt(0)" ::: "memory");
;         } else {
;             XB_SPIN(xb_ld(&bar[XB_XGEN(b.x)]) == gen, bar);
.LBB0_620:
	s_or_b64 exec, exec, s[8:9]
	v_cvt_f32_u32_e32 v5, v3
	s_waitcnt vmcnt(0)
	v_readfirstlane_b32 s3, v4
	v_sub_u32_e32 v4, 0, v3
	v_rcp_iflag_f32_e32 v5, v5
	v_add_u32_e32 v6, s3, v0
	v_mul_f32_e32 v5, 0x4f7ffffe, v5
	v_cvt_u32_f32_e32 v5, v5
	v_mul_lo_u32 v0, v4, v5
	v_mul_hi_u32 v0, v5, v0
	v_add_u32_e32 v0, v5, v0
	v_mul_hi_u32 v0, v6, v0
	v_mul_lo_u32 v4, v0, v3
	v_sub_u32_e32 v4, v6, v4
	v_add_u32_e32 v5, 1, v0
	v_cmp_ge_u32_e32 vcc, v4, v3
	s_nop 1
	v_cndmask_b32_e32 v0, v0, v5, vcc
	v_sub_u32_e32 v5, v4, v3
	v_cndmask_b32_e32 v4, v4, v5, vcc
	v_add_u32_e32 v5, 1, v0
	v_cmp_ge_u32_e32 vcc, v4, v3
	v_add_u32_e32 v4, 1, v6
	s_nop 0
	v_cndmask_b32_e32 v0, v0, v5, vcc
	v_mul_lo_u32 v5, v3, v0
	v_add_u32_e32 v3, v5, v3
	v_cmp_ne_u32_e32 vcc, v4, v3
	s_and_saveexec_b64 s[8:9], vcc
	s_xor_b64 s[8:9], exec, s[8:9]
	s_cbranch_execz .LBB0_636
	v_readlane_b32 s10, v253, 52
	v_readlane_b32 s11, v253, 53
	s_waitcnt lgkmcnt(0)
	s_nop 3
	global_load_dword v2, v1, s[10:11] sc1
	s_waitcnt vmcnt(0)
	v_cmp_eq_u32_e32 vcc, v2, v0
	s_and_saveexec_b64 s[10:11], vcc
	s_cbranch_execz .LBB0_635
	s_mov_b32 s3, 1
	s_mov_b64 s[12:13], 0
	s_branch .LBB0_624

; __device__ __forceinline__ unsigned xb_add(unsigned* p, unsigned v) { return __hip_atomic_fetch_add(p, v, __ATOMIC_RELAXED, __HIP_MEMORY_SCOPE_AGENT); }
; __device__ __forceinline__ void xcd_barrier(const XcdBarrier& b) {
;     ...
;             __builtin_amdgcn_fence(__ATOMIC_ACQUIRE, "agent");
;             xb_add(&bar[XB_XGEN(b.x)], 1u);
;             asm volatile("s_waitcnt vmcnt(0)" ::: "memory");
.LBB0_653:
	s_or_b64 exec, exec, s[8:9]
	s_mov_b64 s[8:9], exec
	v_mbcnt_lo_u32_b32 v0, s8, 0
	v_mbcnt_hi_u32_b32 v0, s9, v0
	v_cmp_eq_u32_e32 vcc, 0, v0
	s_waitcnt vmcnt(0)
	buffer_inv sc1
	s_and_saveexec_b64 s[10:11], vcc
	s_cbranch_execz .LBB0_655
	s_bcnt1_i32_b64 s3, s[8:9]
	v_readlane_b32 s8, v253, 48
	v_mov_b32_e32 v0, s3
	v_readlane_b32 s9, v253, 49
	s_nop 4
	s_nop 0
